# GDN scan chunk loop: the waits around the next-chunk prefetch count out the 8 output stores (vmcnt(8)) instead of draining them (vmcnt(0))
# speedup vs baseline: 1.0028x; 1.0005x over previous
.LBB0_1232:
	s_add_i32 s24, s25, 1
	s_cmp_lt_u32 s24, s35
	s_cselect_b64 s[22:23], -1, 0
	s_cmp_ge_u32 s24, s35
	s_cbranch_scc1 .LBB0_1234
	s_waitcnt vmcnt(8)
	v_lshl_add_u64 v[28:29], s[42:43], 0, v[60:61]
	v_add_co_u32_e32 v20, vcc, 0x8754000, v28
	v_add_u32_e32 v36, s34, v77
	s_nop 0
	v_addc_co_u32_e32 v21, vcc, 0, v29, vcc
	v_cndmask_b32_e64 v36, v78, v36, s[6:7]
	v_add_co_u32_e32 v24, vcc, 0xe3f4000, v28
	v_ashrrev_i32_e32 v37, 31, v36
	s_nop 0
	v_addc_co_u32_e32 v25, vcc, 0, v29, vcc
	v_lshl_add_u64 v[36:37], v[36:37], 0, s[20:21]
	s_add_u32 s72, s42, s26
	v_add_co_u32_e32 v28, vcc, 0xeff4000, v28
	v_lshlrev_b64 v[36:37], 9, v[36:37]
	s_addc_u32 s73, s43, s27
	v_addc_co_u32_e32 v29, vcc, 0, v29, vcc
	v_lshl_add_u64 v[32:33], s[42:43], 0, v[58:59]
	v_lshl_add_u64 v[36:37], v[52:53], 0, v[36:37]
	v_lshl_add_u64 v[40:41], s[42:43], 0, v[56:57]
	v_mov_b64_e32 v[44:45], s[72:73]
	flat_load_dwordx4 v[20:23], v[20:21]
	s_nop 0
	flat_load_dwordx4 v[24:27], v[24:25]
	s_nop 0
	flat_load_dwordx4 v[28:31], v[28:29]
	s_nop 0
	flat_load_dwordx4 v[32:35], v[32:33]
	s_nop 0
	flat_load_dwordx4 v[36:39], v[36:37]
	s_nop 0
	flat_load_dwordx4 v[40:43], v[40:41]
	s_nop 0
	flat_load_dword v66, v[44:45]
.LBB0_1234:
	s_bitcmp1_b32 s25, 0
	s_cselect_b32 s25, 0xb200, 0
	v_or_b32_e32 v102, s25, v68
	s_add_i32 s41, s25, s36
	v_or_b32_e32 v81, s25, v67
	s_add_i32 s41, s41, s37
	v_add_u32_e32 v86, v102, v70
	v_add_u32_e32 v44, s41, v69
	v_add_u32_e32 v106, v81, v70
	v_add_u32_e32 v86, 0x2000, v86
	ds_read_b64 v[46:47], v44 offset:36864
	ds_read_b128 v[90:93], v106
	ds_read2_b64 v[94:97], v86 offset0:128 offset1:132
	s_add_i32 s41, s25, s40
	v_cvt_pk_bf16_f32 v48, v4, v5
	v_cvt_pk_bf16_f32 v49, v6, v7
	v_cvt_pk_bf16_f32 v50, v8, v9
	v_cvt_pk_bf16_f32 v51, v10, v11
	s_waitcnt lgkmcnt(0)
	v_lshlrev_b32_e32 v44, 16, v46
	v_and_b32_e32 v45, 0xffff0000, v46
	v_lshlrev_b32_e32 v46, 16, v47
	v_and_b32_e32 v47, 0xffff0000, v47
	s_add_i32 s41, s41, s37
	v_cvt_pk_bf16_f32 v82, v12, v13
	v_mfma_f32_16x16x32_bf16 v[44:47], v[90:93], v[48:51], v[44:47]
	v_cvt_pk_bf16_f32 v83, v14, v15
	v_cvt_pk_bf16_f32 v84, v16, v17
	v_cvt_pk_bf16_f32 v85, v18, v19
	v_mfma_f32_16x16x32_bf16 v[90:93], v[94:97], v[48:51], v[0:3]
	ds_read_b128 v[94:97], v106 offset:64
	ds_read2_b64 v[98:101], v86 offset0:136 offset1:140
	v_add_u32_e32 v86, s41, v69
	ds_read_b64 v[86:87], v86 offset:36864
	s_waitcnt lgkmcnt(0)
	v_mfma_f32_16x16x32_bf16 v[94:97], v[94:97], v[82:85], v[44:47]
	s_andn2_b64 vcc, exec, s[22:23]
	v_mfma_f32_16x16x32_bf16 v[44:47], v[98:101], v[82:85], v[90:93]
	s_nop 2
	v_lshlrev_b32_e32 v92, 16, v87
	v_and_b32_e32 v93, 0xffff0000, v87
	v_add_u32_e32 v87, v102, v71
	v_lshlrev_b32_e32 v90, 16, v86
	v_and_b32_e32 v91, 0xffff0000, v86
	v_add_u32_e32 v86, v81, v71
	v_add_u32_e32 v87, 0x2000, v87
	ds_read_b128 v[98:101], v86
	ds_read2_b64 v[102:105], v87 offset0:128 offset1:132
	s_waitcnt lgkmcnt(0)
	v_mfma_f32_16x16x32_bf16 v[90:93], v[98:101], v[48:51], v[90:93]
	v_add_u32_e32 v81, v81, v72
	v_mfma_f32_16x16x32_bf16 v[48:51], v[102:105], v[48:51], v[0:3]
	ds_read_b128 v[98:101], v86 offset:64
	ds_read2_b64 v[102:105], v87 offset0:136 offset1:140
	v_mov_b32_e32 v86, s25
	s_waitcnt lgkmcnt(0)
	v_mfma_f32_16x16x32_bf16 v[90:93], v[98:101], v[82:85], v[90:93]
	v_mfma_f32_16x16x32_bf16 v[48:51], v[102:105], v[82:85], v[48:51]
	v_cvt_pk_bf16_f32 v82, v94, v95
	v_cvt_pk_bf16_f32 v83, v96, v97
	s_nop 4
	v_cvt_pk_bf16_f32 v84, v90, v91
	v_cvt_pk_bf16_f32 v85, v92, v93
	ds_write_b128 v79, v[82:85]
	s_waitcnt lgkmcnt(0)
	s_barrier
	ds_read_b128 v[90:93], v80
	s_waitcnt lgkmcnt(0)
	v_cndmask_b32_e64 v97, v93, v85, s[12:13]
	v_cndmask_b32_e64 v96, v92, v84, s[12:13]
	v_cndmask_b32_e64 v95, v91, v83, s[12:13]
	v_cndmask_b32_e64 v94, v90, v82, s[12:13]
	v_cndmask_b32_e64 v85, v85, v93, s[12:13]
	v_cndmask_b32_e64 v84, v84, v92, s[12:13]
	v_cndmask_b32_e64 v83, v83, v91, s[12:13]
	v_cndmask_b32_e64 v82, v82, v90, s[12:13]
	ds_read_b32 v86, v86 offset:45312
	ds_read_b128 v[90:93], v106 offset:18432
	ds_read_b128 v[98:101], v106 offset:18496
	ds_read_b128 v[102:105], v106 offset:20800
	s_waitcnt lgkmcnt(0)
	v_mfma_f32_16x16x32_bf16 v[90:93], v[90:93], v[94:97], v[0:3]
	v_mul_f32_e64 v6, v6, v86
	v_mul_f32_e64 v7, v7, v86
	v_pk_mul_f32 v[4:5], v[4:5], v[86:87] op_sel_hi:[1,0]
	v_pk_mul_f32 v[10:11], v[10:11], v[86:87] op_sel_hi:[1,0]
	v_mfma_f32_16x16x32_bf16 v[90:93], v[98:101], v[82:85], v[90:93]
	ds_read_b128 v[98:101], v106 offset:20736
	v_pk_mul_f32 v[8:9], v[8:9], v[86:87] op_sel_hi:[1,0]
	v_pk_mul_f32 v[14:15], v[14:15], v[86:87] op_sel_hi:[1,0]
	s_waitcnt lgkmcnt(0)
	v_mfma_f32_16x16x32_bf16 v[98:101], v[98:101], v[94:97], v[0:3]
	v_mul_f32_e64 v12, v12, v86
	v_mul_f32_e64 v13, v13, v86
	v_pk_mul_f32 v[18:19], v[18:19], v[86:87] op_sel_hi:[1,0]
	v_pk_mul_f32 v[16:17], v[16:17], v[86:87] op_sel_hi:[1,0]
	v_mfma_f32_16x16x32_bf16 v[98:101], v[102:105], v[82:85], v[98:101]
	ds_read_b128 v[102:105], v81 offset:27648
	v_add_u32_e32 v86, 16, v76
	s_waitcnt lgkmcnt(0)
	v_mfma_f32_16x16x32_bf16 v[4:7], v[102:105], v[94:97], v[4:7]
	ds_read_b128 v[102:105], v81 offset:27712
	s_waitcnt lgkmcnt(0)
	v_mfma_f32_16x16x32_bf16 v[4:7], v[102:105], v[82:85], v[4:7]
	ds_read_b128 v[102:105], v81 offset:29952
	s_waitcnt lgkmcnt(0)
	v_mfma_f32_16x16x32_bf16 v[8:11], v[102:105], v[94:97], v[8:11]
	ds_read_b128 v[102:105], v81 offset:30016
	s_waitcnt lgkmcnt(0)
	v_mfma_f32_16x16x32_bf16 v[8:11], v[102:105], v[82:85], v[8:11]
	ds_read_b128 v[102:105], v81 offset:32256
	s_waitcnt lgkmcnt(0)
	v_mfma_f32_16x16x32_bf16 v[12:15], v[102:105], v[94:97], v[12:15]
	ds_read_b128 v[102:105], v81 offset:32320
	s_waitcnt lgkmcnt(0)
	v_mfma_f32_16x16x32_bf16 v[12:15], v[102:105], v[82:85], v[12:15]
	ds_read_b128 v[102:105], v81 offset:34560
	s_waitcnt lgkmcnt(0)
	v_mfma_f32_16x16x32_bf16 v[16:19], v[102:105], v[94:97], v[16:19]
	ds_read_b128 v[94:97], v81 offset:34624
	v_add_u32_e32 v81, s25, v74
	s_waitcnt lgkmcnt(0)
	v_mfma_f32_16x16x32_bf16 v[16:19], v[94:97], v[82:85], v[16:19]
	ds_read_b128 v[82:85], v81 offset:45056
	v_add_u32_e32 v81, s34, v73
	v_cndmask_b32_e64 v86, v86, v81, s[6:7]
	v_ashrrev_i32_e32 v87, 31, v86
	v_lshl_add_u64 v[86:87], v[86:87], 0, s[20:21]
	s_waitcnt lgkmcnt(0)
	v_fma_f32 v44, v44, v82, v90
	v_bfe_u32 v82, v44, 16, 1
	v_lshlrev_b64 v[86:87], 9, v[86:87]
	v_add3_u32 v44, v44, v82, s60
	v_lshl_add_u64 v[86:87], v[54:55], 0, v[86:87]
	flat_store_short_d16_hi v[86:87], v44
	v_add_u32_e32 v44, 1, v81
	v_xad_u32 v82, v81, -2, s17
	v_cndmask_b32_e64 v86, v82, v44, s[6:7]
	v_ashrrev_i32_e32 v87, 31, v86
	v_fma_f32 v44, v45, v83, v91
	v_lshl_add_u64 v[86:87], v[86:87], 0, s[20:21]
	v_bfe_u32 v45, v44, 16, 1
	v_add3_u32 v82, v44, v45, s60
	v_lshlrev_b64 v[44:45], 9, v[86:87]
	v_lshl_add_u64 v[44:45], v[54:55], 0, v[44:45]
	flat_store_short_d16_hi v[44:45], v82
	v_add_u32_e32 v44, 2, v81
	v_xad_u32 v45, v81, -3, s17
	v_cndmask_b32_e64 v44, v45, v44, s[6:7]
	v_ashrrev_i32_e32 v45, 31, v44
	v_lshl_add_u64 v[44:45], v[44:45], 0, s[20:21]
	v_fma_f32 v46, v46, v84, v92
	v_bfe_u32 v82, v46, 16, 1
	v_lshlrev_b64 v[44:45], 9, v[44:45]
	v_add3_u32 v46, v46, v82, s60
	v_lshl_add_u64 v[44:45], v[54:55], 0, v[44:45]
	flat_store_short_d16_hi v[44:45], v46
	v_add_u32_e32 v44, 3, v81
	v_xad_u32 v45, v81, -4, s17
	v_cndmask_b32_e64 v44, v45, v44, s[6:7]
	v_ashrrev_i32_e32 v45, 31, v44
	v_lshl_add_u64 v[44:45], v[44:45], 0, s[20:21]
	v_fmac_f32_e32 v93, v47, v85
	v_bfe_u32 v46, v93, 16, 1
	v_lshlrev_b64 v[44:45], 9, v[44:45]
	v_add3_u32 v46, v93, v46, s60
	v_lshl_add_u64 v[44:45], v[54:55], 0, v[44:45]
	flat_store_short_d16_hi v[44:45], v46
	v_add_u32_e32 v44, s25, v75
	ds_read_b128 v[44:47], v44 offset:45056
	v_add_u32_e32 v84, 16, v81
	v_cndmask_b32_e64 v82, v76, v84, s[6:7]
	v_ashrrev_i32_e32 v83, 31, v82
	v_lshl_add_u64 v[82:83], v[82:83], 0, s[20:21]
	s_waitcnt lgkmcnt(0)
	v_fma_f32 v44, v48, v44, v98
	v_bfe_u32 v48, v44, 16, 1
	v_lshlrev_b64 v[82:83], 9, v[82:83]
	v_add3_u32 v44, v44, v48, s60
	v_lshl_add_u64 v[82:83], v[54:55], 0, v[82:83]
	flat_store_short_d16_hi v[82:83], v44
	v_add_u32_e32 v44, 17, v81
	v_xad_u32 v48, v84, -2, s17
	v_cndmask_b32_e64 v82, v48, v44, s[6:7]
	v_ashrrev_i32_e32 v83, 31, v82
	v_fma_f32 v44, v49, v45, v99
	v_lshl_add_u64 v[82:83], v[82:83], 0, s[20:21]
	v_bfe_u32 v45, v44, 16, 1
	v_add3_u32 v48, v44, v45, s60
	v_lshlrev_b64 v[44:45], 9, v[82:83]
	v_lshl_add_u64 v[44:45], v[54:55], 0, v[44:45]
	flat_store_short_d16_hi v[44:45], v48
	v_add_u32_e32 v44, 18, v81
	v_xad_u32 v45, v84, -3, s17
	v_cndmask_b32_e64 v44, v45, v44, s[6:7]
	v_ashrrev_i32_e32 v45, 31, v44
	v_lshl_add_u64 v[44:45], v[44:45], 0, s[20:21]
	v_fma_f32 v46, v50, v46, v100
	v_bfe_u32 v48, v46, 16, 1
	v_lshlrev_b64 v[44:45], 9, v[44:45]
	v_add3_u32 v46, v46, v48, s60
	v_lshl_add_u64 v[44:45], v[54:55], 0, v[44:45]
	flat_store_short_d16_hi v[44:45], v46
	v_add_u32_e32 v44, 19, v81
	v_xad_u32 v45, v84, -4, s17
	v_cndmask_b32_e64 v44, v45, v44, s[6:7]
	v_ashrrev_i32_e32 v45, 31, v44
	v_lshl_add_u64 v[44:45], v[44:45], 0, s[20:21]
	v_fmac_f32_e32 v101, v51, v47
	v_bfe_u32 v46, v101, 16, 1
	v_lshlrev_b64 v[44:45], 9, v[44:45]
	v_add3_u32 v46, v101, v46, s60
	v_lshl_add_u64 v[44:45], v[54:55], 0, v[44:45]
	flat_store_short_d16_hi v[44:45], v46
	s_cbranch_vccnz .LBB0_1231
	s_bitcmp1_b32 s24, 0
	s_cselect_b32 s25, 0xb200, 0
	v_add3_u32 v44, s25, v65, v88
	s_waitcnt vmcnt(8)
	ds_write_b128 v44, v[20:23]
	ds_write_b128 v44, v[36:39] offset:9216
	ds_write_b128 v44, v[24:27] offset:18432
	ds_write_b128 v44, v[28:31] offset:27648
	v_add_u32_e32 v44, s25, v64
	ds_write_b128 v44, v[32:35] offset:36864
	s_and_saveexec_b64 s[22:23], s[8:9]
	ds_write_b128 v44, v[40:43] offset:45056
	s_or_b64 exec, exec, s[22:23]
	s_and_saveexec_b64 s[22:23], s[10:11]
	s_cbranch_execz .LBB0_1230
	v_mov_b32_e32 v44, s25
	ds_write_b32 v44, v66 offset:45312
	s_branch .LBB0_1230

.LBB0_2989:
	s_add_i32 s24, s25, 1
	s_cmp_lt_u32 s24, s36
	s_cselect_b64 s[22:23], -1, 0
	s_cmp_ge_u32 s24, s36
	s_cbranch_scc1 .LBB0_2991
	s_waitcnt vmcnt(8)
	v_lshl_add_u64 v[28:29], s[42:43], 0, v[60:61]
	v_add_co_u32_e32 v20, vcc, 0x8754000, v28
	v_add_u32_e32 v36, s35, v77
	s_nop 0
	v_addc_co_u32_e32 v21, vcc, 0, v29, vcc
	v_cndmask_b32_e64 v36, v78, v36, s[6:7]
	v_add_co_u32_e32 v24, vcc, 0xe3f4000, v28
	v_ashrrev_i32_e32 v37, 31, v36
	s_nop 0
	v_addc_co_u32_e32 v25, vcc, 0, v29, vcc
	v_lshl_add_u64 v[36:37], v[36:37], 0, s[20:21]
	s_add_u32 s64, s42, s26
	v_add_co_u32_e32 v28, vcc, 0xeff4000, v28
	v_lshlrev_b64 v[36:37], 9, v[36:37]
	s_addc_u32 s65, s43, s27
	v_addc_co_u32_e32 v29, vcc, 0, v29, vcc
	v_lshl_add_u64 v[32:33], s[42:43], 0, v[58:59]
	v_lshl_add_u64 v[36:37], v[52:53], 0, v[36:37]
	v_lshl_add_u64 v[40:41], s[42:43], 0, v[56:57]
	v_mov_b64_e32 v[44:45], s[64:65]
	flat_load_dwordx4 v[20:23], v[20:21]
	s_nop 0
	flat_load_dwordx4 v[24:27], v[24:25]
	s_nop 0
	flat_load_dwordx4 v[28:31], v[28:29]
	s_nop 0
	flat_load_dwordx4 v[32:35], v[32:33]
	s_nop 0
	flat_load_dwordx4 v[36:39], v[36:37]
	s_nop 0
	flat_load_dwordx4 v[40:43], v[40:41]
	s_nop 0
	flat_load_dword v66, v[44:45]
.LBB0_2991:
	s_bitcmp1_b32 s25, 0
	s_cselect_b32 s25, 0xb200, 0
	v_or_b32_e32 v102, s25, v68
	s_add_i32 s44, s25, s37
	v_or_b32_e32 v81, s25, v67
	s_add_i32 s44, s44, s40
	v_add_u32_e32 v86, v102, v70
	v_add_u32_e32 v44, s44, v69
	v_add_u32_e32 v106, v81, v70
	v_add_u32_e32 v86, 0x2000, v86
	ds_read_b64 v[46:47], v44 offset:36864
	ds_read_b128 v[90:93], v106
	ds_read2_b64 v[94:97], v86 offset0:128 offset1:132
	s_add_i32 s44, s25, s41
	v_cvt_pk_bf16_f32 v48, v8, v9
	v_cvt_pk_bf16_f32 v49, v10, v11
	v_cvt_pk_bf16_f32 v50, v4, v5
	v_cvt_pk_bf16_f32 v51, v6, v7
	s_waitcnt lgkmcnt(0)
	v_lshlrev_b32_e32 v44, 16, v46
	v_and_b32_e32 v45, 0xffff0000, v46
	v_lshlrev_b32_e32 v46, 16, v47
	v_and_b32_e32 v47, 0xffff0000, v47
	s_add_i32 s44, s44, s40
	v_cvt_pk_bf16_f32 v82, v12, v13
	v_mfma_f32_16x16x32_bf16 v[44:47], v[90:93], v[48:51], v[44:47]
	v_cvt_pk_bf16_f32 v83, v14, v15
	v_cvt_pk_bf16_f32 v84, v16, v17
	v_cvt_pk_bf16_f32 v85, v18, v19
	v_mfma_f32_16x16x32_bf16 v[90:93], v[94:97], v[48:51], v[0:3]
	ds_read_b128 v[94:97], v106 offset:64
	ds_read2_b64 v[98:101], v86 offset0:136 offset1:140
	v_add_u32_e32 v86, s44, v69
	ds_read_b64 v[86:87], v86 offset:36864
	s_waitcnt lgkmcnt(0)
	v_mfma_f32_16x16x32_bf16 v[94:97], v[94:97], v[82:85], v[44:47]
	s_andn2_b64 vcc, exec, s[22:23]
	v_mfma_f32_16x16x32_bf16 v[44:47], v[98:101], v[82:85], v[90:93]
	s_nop 2
	v_lshlrev_b32_e32 v92, 16, v87
	v_and_b32_e32 v93, 0xffff0000, v87
	v_add_u32_e32 v87, v102, v71
	v_lshlrev_b32_e32 v90, 16, v86
	v_and_b32_e32 v91, 0xffff0000, v86
	v_add_u32_e32 v86, v81, v71
	v_add_u32_e32 v87, 0x2000, v87
	ds_read_b128 v[98:101], v86
	ds_read2_b64 v[102:105], v87 offset0:128 offset1:132
	s_waitcnt lgkmcnt(0)
	v_mfma_f32_16x16x32_bf16 v[90:93], v[98:101], v[48:51], v[90:93]
	v_add_u32_e32 v81, v81, v72
	v_mfma_f32_16x16x32_bf16 v[48:51], v[102:105], v[48:51], v[0:3]
	ds_read_b128 v[98:101], v86 offset:64
	ds_read2_b64 v[102:105], v87 offset0:136 offset1:140
	v_mov_b32_e32 v86, s25
	s_waitcnt lgkmcnt(0)
	v_mfma_f32_16x16x32_bf16 v[90:93], v[98:101], v[82:85], v[90:93]
	v_mfma_f32_16x16x32_bf16 v[48:51], v[102:105], v[82:85], v[48:51]
	v_cvt_pk_bf16_f32 v82, v94, v95
	v_cvt_pk_bf16_f32 v83, v96, v97
	s_nop 4
	v_cvt_pk_bf16_f32 v84, v90, v91
	v_cvt_pk_bf16_f32 v85, v92, v93
	ds_write_b128 v79, v[82:85]
	s_waitcnt lgkmcnt(0)
	s_barrier
	ds_read_b128 v[90:93], v80
	s_waitcnt lgkmcnt(0)
	v_cndmask_b32_e64 v97, v93, v85, s[12:13]
	v_cndmask_b32_e64 v96, v92, v84, s[12:13]
	v_cndmask_b32_e64 v95, v91, v83, s[12:13]
	v_cndmask_b32_e64 v94, v90, v82, s[12:13]
	v_cndmask_b32_e64 v85, v85, v93, s[12:13]
	v_cndmask_b32_e64 v84, v84, v92, s[12:13]
	v_cndmask_b32_e64 v83, v83, v91, s[12:13]
	v_cndmask_b32_e64 v82, v82, v90, s[12:13]
	ds_read_b32 v86, v86 offset:45312
	ds_read_b128 v[90:93], v106 offset:18432
	ds_read_b128 v[98:101], v106 offset:18496
	ds_read_b128 v[102:105], v106 offset:20800
	s_waitcnt lgkmcnt(0)
	v_mfma_f32_16x16x32_bf16 v[90:93], v[90:93], v[94:97], v[0:3]
	v_mul_f32_e64 v10, v10, v86
	v_mul_f32_e64 v11, v11, v86
	v_pk_mul_f32 v[8:9], v[8:9], v[86:87] op_sel_hi:[1,0]
	v_pk_mul_f32 v[6:7], v[6:7], v[86:87] op_sel_hi:[1,0]
	v_mfma_f32_16x16x32_bf16 v[90:93], v[98:101], v[82:85], v[90:93]
	ds_read_b128 v[98:101], v106 offset:20736
	v_pk_mul_f32 v[4:5], v[4:5], v[86:87] op_sel_hi:[1,0]
	v_pk_mul_f32 v[14:15], v[14:15], v[86:87] op_sel_hi:[1,0]
	s_waitcnt lgkmcnt(0)
	v_mfma_f32_16x16x32_bf16 v[98:101], v[98:101], v[94:97], v[0:3]
	v_mul_f32_e64 v12, v12, v86
	v_mul_f32_e64 v13, v13, v86
	v_pk_mul_f32 v[18:19], v[18:19], v[86:87] op_sel_hi:[1,0]
	v_pk_mul_f32 v[16:17], v[16:17], v[86:87] op_sel_hi:[1,0]
	v_mfma_f32_16x16x32_bf16 v[98:101], v[102:105], v[82:85], v[98:101]
	ds_read_b128 v[102:105], v81 offset:27648
	v_add_u32_e32 v86, 16, v76
	s_waitcnt lgkmcnt(0)
	v_mfma_f32_16x16x32_bf16 v[8:11], v[102:105], v[94:97], v[8:11]
	ds_read_b128 v[102:105], v81 offset:27712
	s_waitcnt lgkmcnt(0)
	v_mfma_f32_16x16x32_bf16 v[8:11], v[102:105], v[82:85], v[8:11]
	ds_read_b128 v[102:105], v81 offset:29952
	s_waitcnt lgkmcnt(0)
	v_mfma_f32_16x16x32_bf16 v[4:7], v[102:105], v[94:97], v[4:7]
	ds_read_b128 v[102:105], v81 offset:30016
	s_waitcnt lgkmcnt(0)
	v_mfma_f32_16x16x32_bf16 v[4:7], v[102:105], v[82:85], v[4:7]
	ds_read_b128 v[102:105], v81 offset:32256
	s_waitcnt lgkmcnt(0)
	v_mfma_f32_16x16x32_bf16 v[12:15], v[102:105], v[94:97], v[12:15]
	ds_read_b128 v[102:105], v81 offset:32320
	s_waitcnt lgkmcnt(0)
	v_mfma_f32_16x16x32_bf16 v[12:15], v[102:105], v[82:85], v[12:15]
	ds_read_b128 v[102:105], v81 offset:34560
	s_waitcnt lgkmcnt(0)
	v_mfma_f32_16x16x32_bf16 v[16:19], v[102:105], v[94:97], v[16:19]
	ds_read_b128 v[94:97], v81 offset:34624
	v_add_u32_e32 v81, s25, v74
	s_waitcnt lgkmcnt(0)
	v_mfma_f32_16x16x32_bf16 v[16:19], v[94:97], v[82:85], v[16:19]
	ds_read_b128 v[82:85], v81 offset:45056
	v_add_u32_e32 v81, s35, v73
	v_cndmask_b32_e64 v86, v86, v81, s[6:7]
	v_ashrrev_i32_e32 v87, 31, v86
	v_lshl_add_u64 v[86:87], v[86:87], 0, s[20:21]
	s_waitcnt lgkmcnt(0)
	v_fma_f32 v44, v44, v82, v90
	v_bfe_u32 v82, v44, 16, 1
	v_lshlrev_b64 v[86:87], 9, v[86:87]
	v_add3_u32 v44, v44, v82, s93
	v_lshl_add_u64 v[86:87], v[54:55], 0, v[86:87]
	flat_store_short_d16_hi v[86:87], v44
	v_add_u32_e32 v44, 1, v81
	v_xad_u32 v82, v81, -2, s17
	v_cndmask_b32_e64 v86, v82, v44, s[6:7]
	v_ashrrev_i32_e32 v87, 31, v86
	v_fma_f32 v44, v45, v83, v91
	v_lshl_add_u64 v[86:87], v[86:87], 0, s[20:21]
	v_bfe_u32 v45, v44, 16, 1
	v_add3_u32 v82, v44, v45, s93
	v_lshlrev_b64 v[44:45], 9, v[86:87]
	v_lshl_add_u64 v[44:45], v[54:55], 0, v[44:45]
	flat_store_short_d16_hi v[44:45], v82
	v_add_u32_e32 v44, 2, v81
	v_xad_u32 v45, v81, -3, s17
	v_cndmask_b32_e64 v44, v45, v44, s[6:7]
	v_ashrrev_i32_e32 v45, 31, v44
	v_lshl_add_u64 v[44:45], v[44:45], 0, s[20:21]
	v_fma_f32 v46, v46, v84, v92
	v_bfe_u32 v82, v46, 16, 1
	v_lshlrev_b64 v[44:45], 9, v[44:45]
	v_add3_u32 v46, v46, v82, s93
	v_lshl_add_u64 v[44:45], v[54:55], 0, v[44:45]
	flat_store_short_d16_hi v[44:45], v46
	v_add_u32_e32 v44, 3, v81
	v_xad_u32 v45, v81, -4, s17
	v_cndmask_b32_e64 v44, v45, v44, s[6:7]
	v_ashrrev_i32_e32 v45, 31, v44
	v_lshl_add_u64 v[44:45], v[44:45], 0, s[20:21]
	v_fmac_f32_e32 v93, v47, v85
	v_bfe_u32 v46, v93, 16, 1
	v_lshlrev_b64 v[44:45], 9, v[44:45]
	v_add3_u32 v46, v93, v46, s93
	v_lshl_add_u64 v[44:45], v[54:55], 0, v[44:45]
	flat_store_short_d16_hi v[44:45], v46
	v_add_u32_e32 v44, s25, v75
	ds_read_b128 v[44:47], v44 offset:45056
	v_add_u32_e32 v84, 16, v81
	v_cndmask_b32_e64 v82, v76, v84, s[6:7]
	v_ashrrev_i32_e32 v83, 31, v82
	v_lshl_add_u64 v[82:83], v[82:83], 0, s[20:21]
	s_waitcnt lgkmcnt(0)
	v_fma_f32 v44, v48, v44, v98
	v_bfe_u32 v48, v44, 16, 1
	v_lshlrev_b64 v[82:83], 9, v[82:83]
	v_add3_u32 v44, v44, v48, s93
	v_lshl_add_u64 v[82:83], v[54:55], 0, v[82:83]
	flat_store_short_d16_hi v[82:83], v44
	v_add_u32_e32 v44, 17, v81
	v_xad_u32 v48, v84, -2, s17
	v_cndmask_b32_e64 v82, v48, v44, s[6:7]
	v_ashrrev_i32_e32 v83, 31, v82
	v_fma_f32 v44, v49, v45, v99
	v_lshl_add_u64 v[82:83], v[82:83], 0, s[20:21]
	v_bfe_u32 v45, v44, 16, 1
	v_add3_u32 v48, v44, v45, s93
	v_lshlrev_b64 v[44:45], 9, v[82:83]
	v_lshl_add_u64 v[44:45], v[54:55], 0, v[44:45]
	flat_store_short_d16_hi v[44:45], v48
	v_add_u32_e32 v44, 18, v81
	v_xad_u32 v45, v84, -3, s17
	v_cndmask_b32_e64 v44, v45, v44, s[6:7]
	v_ashrrev_i32_e32 v45, 31, v44
	v_lshl_add_u64 v[44:45], v[44:45], 0, s[20:21]
	v_fma_f32 v46, v50, v46, v100
	v_bfe_u32 v48, v46, 16, 1
	v_lshlrev_b64 v[44:45], 9, v[44:45]
	v_add3_u32 v46, v46, v48, s93
	v_lshl_add_u64 v[44:45], v[54:55], 0, v[44:45]
	flat_store_short_d16_hi v[44:45], v46
	v_add_u32_e32 v44, 19, v81
	v_xad_u32 v45, v84, -4, s17
	v_cndmask_b32_e64 v44, v45, v44, s[6:7]
	v_ashrrev_i32_e32 v45, 31, v44
	v_lshl_add_u64 v[44:45], v[44:45], 0, s[20:21]
	v_fmac_f32_e32 v101, v51, v47
	v_bfe_u32 v46, v101, 16, 1
	v_lshlrev_b64 v[44:45], 9, v[44:45]
	v_add3_u32 v46, v101, v46, s93
	v_lshl_add_u64 v[44:45], v[54:55], 0, v[44:45]
	flat_store_short_d16_hi v[44:45], v46
	s_cbranch_vccnz .LBB0_2988
	s_bitcmp1_b32 s24, 0
	s_cselect_b32 s25, 0xb200, 0
	v_add3_u32 v44, s25, v65, v88
	s_waitcnt vmcnt(8)
	ds_write_b128 v44, v[20:23]
	ds_write_b128 v44, v[36:39] offset:9216
	ds_write_b128 v44, v[24:27] offset:18432
	ds_write_b128 v44, v[28:31] offset:27648
	v_add_u32_e32 v44, s25, v64
	ds_write_b128 v44, v[32:35] offset:36864
	s_and_saveexec_b64 s[22:23], s[8:9]
	ds_write_b128 v44, v[40:43] offset:45056
	s_or_b64 exec, exec, s[22:23]
	s_and_saveexec_b64 s[22:23], s[10:11]
	s_cbranch_execz .LBB0_2987
	v_mov_b32_e32 v44, s25
	ds_write_b32 v44, v66 offset:45312
	s_branch .LBB0_2987
